# radix-select top-k (exact same selection) replaces 64x64 rank loop in NSA; plus earlier epilogue load hoists, rcp sigmoid, P3 ladder
# speedup vs baseline: 1.0144x; 1.0144x over previous
;     ...
;     if (sub < 2) {
;         float c[8], s[8]; load8f(rt, c); load8f(rt + 8, s);
; __global__ void __launch_bounds__(NTHR, 2) hybrid_fwd(Args args) {
;     ...
;             {
;                 const u32x4 zero4 = (u32x4){0, 0, 0, 0};
;                 const int kch = (lane < 16) ? 308 + lane : 340 + (lane - 16);
;                 int m = gw;
;                 for (; m + NGW < T; m += 2 * NGW) {
;                     R1_LOAD(A, m) R1_LOAD(B, m + NGW)
;                     R1_COMPUTE(A, m); R1_COMPUTE(B, m + NGW);
;                 }
;                 if (m < T) { R1_LOAD(A, m) R1_COMPUTE(A, m); }
.LBB0_384:
	v_and_b32_e32 v2, 64, v253
	v_add_u32_e32 v2, 64, v2
	v_xor_b32_e32 v3, 1, v253
	v_cmp_lt_i32_e32 vcc, v3, v2
	s_waitcnt lgkmcnt(0)
	s_add_u32 s44, s16, 0x2700000
	s_load_dwordx2 s[52:53], s[12:13], 0x50
	s_load_dwordx4 s[68:71], s[12:13], 0xb8
	v_cndmask_b32_e32 v3, v253, v3, vcc
	s_addc_u32 s45, s17, 0
	v_lshlrev_b32_e32 v99, 2, v3
	v_xor_b32_e32 v3, 2, v253
	s_add_u32 s24, s16, 0x10000
	v_cmp_lt_i32_e32 vcc, v3, v2
	s_addc_u32 s29, s17, 0
	s_ashr_i32 s27, s26, 31
	v_cndmask_b32_e32 v3, v253, v3, vcc
	v_lshlrev_b32_e32 v100, 2, v3
	v_xor_b32_e32 v3, 4, v253
	s_lshl_b64 s[30:31], s[26:27], 10
	s_lshl_b64 s[56:57], s[26:27], 12
	v_cmp_lt_i32_e32 vcc, v3, v2
	s_waitcnt lgkmcnt(0)
	s_add_u32 s52, s52, s56
	s_addc_u32 s53, s53, s57
	v_cndmask_b32_e32 v3, v253, v3, vcc
	v_mov_b32_e32 v57, v1
	v_lshlrev_b32_e32 v101, 2, v3
	v_xor_b32_e32 v3, 8, v253
	v_lshl_add_u64 v[60:61], s[52:53], 0, v[56:57]
	s_lshl_b64 s[52:53], s[26:27], 8
	v_cmp_lt_i32_e32 vcc, v3, v2
	s_add_u32 s56, s68, s52
	s_addc_u32 s57, s69, s53
	v_cndmask_b32_e32 v3, v253, v3, vcc
	v_lshlrev_b32_e32 v102, 2, v3
	v_xor_b32_e32 v3, 16, v253
	s_add_u32 s52, s70, s52
	v_cmp_lt_i32_e32 vcc, v3, v2
	v_mov_b32_e32 v53, v1
	s_addc_u32 s53, s71, s53
	v_cndmask_b32_e32 v3, v253, v3, vcc
	v_lshl_add_u64 v[64:65], s[52:53], 0, v[52:53]
	s_lshl_b32 s27, s50, 4
	v_mov_b32_e32 v59, v1
	s_mul_i32 s53, s18, 0x1800
	v_lshlrev_b32_e32 v103, 2, v3
	v_xor_b32_e32 v3, 32, v253
	v_lshl_add_u64 v[66:67], s[44:45], 0, v[58:59]
	s_mul_hi_i32 s52, s18, 0x1800
	s_add_u32 s44, s44, s53
	v_cmp_lt_i32_e32 vcc, v3, v2
	s_addc_u32 s45, s45, s52
	s_add_i32 s52, s50, s51
	v_cndmask_b32_e32 v2, v253, v3, vcc
	v_lshl_add_u64 v[62:63], s[56:57], 0, v[52:53]
	s_lshl_b32 s56, s52, 3
	s_lshl_b32 s51, s51, 7
	s_lshl_b32 s52, s19, 4
	v_lshlrev_b32_e32 v104, 2, v2
	s_mul_hi_i32 s54, s26, 0x600
	s_mul_i32 s55, s26, 0x600
	s_movk_i32 s70, 0x5ee0
	v_lshl_add_u64 v[68:69], s[44:45], 0, v[58:59]
	s_mul_i32 s44, s50, 0x18000
	s_mul_hi_i32 s45, s27, 0x1800
	v_mov_b32_e32 v51, v1
	s_add_i32 s57, s51, s52
	s_lshl_b32 s62, s50, 8
	s_mov_b32 s63, s18
	s_mov_b32 s32, 0
	s_branch .LBB0_386
.LBB0_385:
	s_mov_b32 s32, 1
	s_or_b64 exec, exec, s[50:51]
	s_add_i32 s63, s63, s27
	s_add_i32 s19, s19, s27
	s_add_i32 s64, s63, s20
	s_add_i32 s50, s56, s19
	s_add_i32 s57, s57, s62
	s_cmp_lt_i32 s50, 0x8000
	v_lshl_add_u64 v[68:69], v[68:69], 0, s[44:45]
	s_cbranch_scc0 .LBB0_418
.LBB0_386:
	s_and_b32 s100, s57, 0xfff0
	s_lshl_b32 s100, s100, 2
	s_add_u32 s100, s24, s100
	s_addc_u32 s101, s29, 0
	global_load_dwordx4 v[158:161], v1, s[100:101]
	global_load_dwordx4 v[162:165], v1, s[100:101] offset:16
	global_load_dwordx4 v[166:169], v1, s[100:101] offset:32
	global_load_dwordx4 v[170:173], v1, s[100:101] offset:48
	s_lshl_b32 s98, s64, 6
	s_and_b32 s98, s98, 0x3ffc0
	s_add_u32 s98, s24, s98
	s_addc_u32 s99, s29, 0
	global_load_dwordx4 v[174:177], v1, s[98:99]
	global_load_dwordx4 v[178:181], v1, s[98:99] offset:16
	global_load_dwordx4 v[182:185], v1, s[98:99] offset:32
	global_load_dwordx4 v[186:189], v1, s[98:99] offset:48
	global_load_dwordx4 v[46:49], v[68:69], off
	v_mov_b32_e32 v26, 0
	v_mov_b32_e32 v42, 0
	v_mov_b32_e32 v43, 0
	v_mov_b32_e32 v44, 0
	v_mov_b32_e32 v45, 0
	s_and_saveexec_b64 s[50:51], s[6:7]
	s_cbranch_execz .LBB0_388
	global_load_dwordx4 v[42:45], v[68:69], off offset:1024

.LBB0_398:
	s_or_b64 exec, exec, s[50:51]
	v_mov_b32_e32 v85, v91
	v_mov_b32_e32 v83, v93
	s_waitcnt vmcnt(0)
	s_cmp_lg_u32 s32, 0
	s_cbranch_scc1 .Lld_p3_1
	global_load_dwordx4 v[114:117], v[94:95], off offset:16
	global_load_dwordx4 v[110:113], v[94:95], off
	s_waitcnt vmcnt(0)
.Lld_p3_1:
	v_mov_b64_e32 v[90:91], v[114:115]
	v_mov_b64_e32 v[92:93], v[116:117]
	v_mov_b64_e32 v[106:107], v[110:111]
	v_mov_b64_e32 v[108:109], v[112:113]
	v_mov_b32_e32 v89, v53
	v_mov_b32_e32 v87, v55
	v_pk_mul_f32 v[88:89], v[80:81], v[88:89] op_sel_hi:[0,1]
	v_pk_mul_f32 v[86:87], v[80:81], v[86:87] op_sel_hi:[0,1]
	v_pk_mul_f32 v[84:85], v[80:81], v[84:85] op_sel_hi:[0,1]
	v_pk_mul_f32 v[82:83], v[80:81], v[82:83] op_sel_hi:[0,1]
	v_pk_mul_f32 v[84:85], v[90:91], v[84:85]
	v_pk_mul_f32 v[88:89], v[106:107], v[88:89]
	v_pk_mul_f32 v[86:87], v[108:109], v[86:87]
	v_pk_mul_f32 v[90:91], v[92:93], v[82:83]
	v_cvt_pk_bf16_f32 v82, v88, v89
	v_cvt_pk_bf16_f32 v83, v86, v87
	v_cvt_pk_bf16_f32 v84, v84, v85
	v_cvt_pk_bf16_f32 v85, v90, v91
	global_store_dwordx4 v[68:69], v[82:85], off
	s_and_saveexec_b64 s[50:51], s[6:7]
	s_cbranch_execz .LBB0_400
	s_load_dwordx2 s[52:53], s[12:13], 0x20
	v_mov_b32_e32 v79, v47
	v_mov_b32_e32 v47, v81
	v_mov_b32_e32 v49, v43
	v_mov_b32_e32 v43, v45
	s_waitcnt lgkmcnt(0)
	s_add_u32 s52, s52, s30
	s_addc_u32 s53, s53, s31
	s_cmp_lg_u32 s32, 0
	s_cbranch_scc1 .Lld_p3_2
	global_load_dwordx4 v[122:125], v74, s[52:53] offset:528
	global_load_dwordx4 v[118:121], v74, s[52:53] offset:512
	s_waitcnt vmcnt(0)
.Lld_p3_2:
	v_mov_b64_e32 v[80:81], v[122:123]
	v_mov_b64_e32 v[82:83], v[124:125]
	v_mov_b64_e32 v[84:85], v[118:119]
	v_mov_b64_e32 v[86:87], v[120:121]
	v_pk_mul_f32 v[78:79], v[44:45], v[78:79] op_sel_hi:[0,1]
	v_pk_mul_f32 v[48:49], v[44:45], v[48:49] op_sel_hi:[0,1]
	v_pk_mul_f32 v[46:47], v[44:45], v[46:47] op_sel_hi:[0,1]
	v_pk_mul_f32 v[42:43], v[44:45], v[42:43] op_sel_hi:[0,1]
	v_pk_mul_f32 v[46:47], v[80:81], v[46:47]
	v_pk_mul_f32 v[78:79], v[84:85], v[78:79]
	v_pk_mul_f32 v[48:49], v[86:87], v[48:49]
	v_pk_mul_f32 v[80:81], v[82:83], v[42:43]
	v_cvt_pk_bf16_f32 v42, v78, v79
	v_cvt_pk_bf16_f32 v43, v48, v49
	v_cvt_pk_bf16_f32 v44, v46, v47
	v_cvt_pk_bf16_f32 v45, v80, v81
	global_store_dwordx4 v[68:69], v[42:45], off offset:1024
.LBB0_400:
	s_or_b64 exec, exec, s[50:51]
	s_waitcnt lgkmcnt(0)
	v_lshlrev_b32_e32 v57, 16, v38
	v_and_b32_e32 v59, 0xffff0000, v38
	v_lshlrev_b32_e32 v73, 16, v39
	v_and_b32_e32 v75, 0xffff0000, v39
	v_lshlrev_b32_e32 v84, 16, v40
	v_and_b32_e32 v85, 0xffff0000, v40
	v_lshlrev_b32_e32 v55, 16, v41
	v_and_b32_e32 v53, 0xffff0000, v41
	s_cmp_lg_u32 s32, 0
	s_cbranch_scc1 .Lld_p3_3
	global_load_dwordx4 v[130:133], v[60:61], off offset:16
	global_load_dwordx4 v[126:129], v[60:61], off
	global_load_dwordx4 v[138:141], v[60:61], off offset:2064
	global_load_dwordx4 v[134:137], v[60:61], off offset:2048
	s_waitcnt vmcnt(0)
.Lld_p3_3:
	v_mov_b64_e32 v[38:39], v[130:131]
	v_mov_b64_e32 v[40:41], v[132:133]
	v_mov_b64_e32 v[46:47], v[126:127]
	v_mov_b64_e32 v[48:49], v[128:129]
	v_mov_b64_e32 v[42:43], v[138:139]
	v_mov_b64_e32 v[44:45], v[140:141]
	v_mov_b64_e32 v[78:79], v[134:135]
	v_mov_b64_e32 v[80:81], v[136:137]
	v_lshlrev_b32_e32 v82, 16, v34
	v_and_b32_e32 v83, 0xffff0000, v34
	s_and_b32 s50, s57, 0xfff0
	s_lshl_b32 s50, s50, 2
	s_add_u32 s50, s24, s50
	s_addc_u32 s51, s29, 0
	v_pk_add_f32 v[46:47], v[46:47], v[82:83]
	v_add_f32_e32 v42, v42, v84
	v_add_f32_e32 v57, v78, v57
	v_mul_f32_e32 v57, 0xbfb8aa3b, v57
	v_exp_f32_e32 v78, v57
	v_add_f32_e32 v57, v79, v59
	v_mul_f32_e32 v57, 0xbfb8aa3b, v57
	v_exp_f32_e32 v79, v57
	v_add_f32_e32 v43, v43, v85
	v_mul_f32_e32 v42, 0xbfb8aa3b, v42
	v_mul_f32_e32 v43, 0xbfb8aa3b, v43
	v_pk_add_f32 v[78:79], v[78:79], 1.0 op_sel_hi:[1,0]
	v_exp_f32_e32 v42, v42
	v_exp_f32_e32 v43, v43
	v_rcp_f32_e32 v79, v79
	v_pk_add_f32 v[42:43], v[42:43], 1.0 op_sel_hi:[1,0]
	v_rcp_f32_e32 v78, v78
	v_add_f32_e32 v34, v80, v73
	v_mul_f32_e32 v34, 0xbfb8aa3b, v34
	v_pk_mul_f32 v[46:47], v[46:47], v[78:79]
	v_exp_f32_e32 v78, v34
	v_add_f32_e32 v34, v81, v75
	v_mul_f32_e32 v34, 0xbfb8aa3b, v34
	v_exp_f32_e32 v79, v34
	v_lshlrev_b32_e32 v34, 16, v35
	v_and_b32_e32 v35, 0xffff0000, v35
	v_pk_add_f32 v[34:35], v[48:49], v[34:35]
	v_pk_add_f32 v[48:49], v[78:79], 1.0 op_sel_hi:[1,0]
	s_nop 0
	s_nop 0
	v_rcp_f32_e32 v49, v49
	s_nop 0
	v_rcp_f32_e32 v48, v48
	s_nop 0
	v_pk_mul_f32 v[34:35], v[34:35], v[48:49]
	v_lshlrev_b32_e32 v48, 16, v36
	v_and_b32_e32 v49, 0xffff0000, v36
	v_pk_add_f32 v[38:39], v[38:39], v[48:49]
	s_nop 0
	v_rcp_f32_e32 v43, v43
	s_nop 0
	v_rcp_f32_e32 v42, v42
	v_add_f32_e32 v36, v44, v55
	v_mul_f32_e32 v36, 0xbfb8aa3b, v36
	v_pk_mul_f32 v[38:39], v[38:39], v[42:43]
	v_exp_f32_e32 v42, v36
	v_add_f32_e32 v36, v45, v53
	v_mul_f32_e32 v36, 0xbfb8aa3b, v36
	v_exp_f32_e32 v43, v36
	v_lshlrev_b32_e32 v36, 16, v37
	v_and_b32_e32 v37, 0xffff0000, v37
	v_pk_add_f32 v[36:37], v[40:41], v[36:37]
	v_pk_add_f32 v[40:41], v[42:43], 1.0 op_sel_hi:[1,0]
	v_cvt_pk_bf16_f32 v38, v38, v39
	v_and_b32_e32 v49, 0xffff0000, v33
	v_mov_b32_e32 v79, v49
	v_rcp_f32_e32 v41, v41
	s_nop 0
	v_rcp_f32_e32 v40, v40
	s_nop 0
	v_pk_mul_f32 v[40:41], v[36:37], v[40:41]
	v_cvt_pk_bf16_f32 v36, v46, v47
	v_cvt_pk_bf16_f32 v37, v34, v35
	v_cvt_pk_bf16_f32 v39, v40, v41
	global_store_dwordx4 v[68:69], v[36:39], off offset:1344
	s_cmp_lg_u32 s32, 0
	s_cbranch_scc1 .Lld_p3_4
	global_load_dwordx4 v[146:149], v[62:63], off offset:16
	global_load_dwordx4 v[142:145], v[62:63], off
	s_waitcnt vmcnt(0)
; DI void unpack8(const u32x4 w, float (&f)[8]) { f[0] = bflo(w.x); f[1] = bfhi(w.x); f[2] = bflo(w.y); f[3] = bfhi(w.y); f[4] = bflo(w.z); f[5] = bfhi(w.z); f[6] = bflo(w.w); f[7] = bfhi(w.w); }
; DI u32x4 pack8(const float (&f)[8]) { u32x4 w; w.x = pk2(f[0], f[1]); w.y = pk2(f[2], f[3]); w.z = pk2(f[4], f[5]); w.w = pk2(f[6], f[7]); return w; }
; DI float ssq8(const float (&f)[8]) { return ((f[0] * f[0] + f[1] * f[1]) + (f[2] * f[2] + f[3] * f[3])) + ((f[4] * f[4] + f[5] * f[5]) + (f[6] * f[6] + f[7] * f[7])); }
;     float q[8]; unpack8(w, q);
;     float ss = ssq8(q); ss += __shfl_xor(ss, 1); ss += __shfl_xor(ss, 2); ss += __shfl_xor(ss, 4);
;     const float r = rsqrtf(ss * (1.f / 64.f) + EPS) * oscale;
;     const int sub = lane & 7;
;     float g[8]; load8f(gain + 8 * sub, g);
;     float y[8], p[8];
; #pragma unroll
;     for (int e = 0; e < 8; ++e) y[e] = q[e] * r * g[e];
; #pragma unroll
;     for (int e = 0; e < 8; ++e) p[e] = __shfl_xor(y[e], 1);
;     if (sub < 2) {
;         float c[8], s[8]; load8f(rt, c); load8f(rt + 8, s);
; #pragma unroll
;         for (int e = 0; e < 8; ++e) y[e] = (sub == 0) ? (y[e] * c[e] - p[e] * s[e]) : (y[e] * c[e] + p[e] * s[e]);
;     }
;     return pack8(y);
.Lld_p3_4:
	v_mov_b64_e32 v[34:35], v[146:147]
	v_mov_b64_e32 v[36:37], v[148:149]
	v_mov_b64_e32 v[38:39], v[142:143]
	v_mov_b64_e32 v[40:41], v[144:145]
	v_and_b32_e32 v43, 0xffff0000, v30
	v_and_b32_e32 v47, 0xffff0000, v32
	v_lshlrev_b32_e32 v42, 16, v30
	v_and_b32_e32 v45, 0xffff0000, v31
	v_lshlrev_b32_e32 v46, 16, v32
	v_lshlrev_b32_e32 v48, 16, v33
	v_mov_b32_e32 v32, v43
	v_mov_b32_e32 v33, v47
	v_lshlrev_b32_e32 v44, 16, v31
	v_mov_b32_e32 v30, v42
	v_mov_b32_e32 v31, v46
	v_pk_mul_f32 v[32:33], v[32:33], v[32:33]
	v_mov_b32_e32 v78, v45
	v_pk_fma_f32 v[30:31], v[30:31], v[30:31], v[32:33]
	v_mov_b32_e32 v32, v44
	v_mov_b32_e32 v33, v48
	v_pk_mul_f32 v[78:79], v[78:79], v[78:79]
	s_nop 0
	v_pk_fma_f32 v[32:33], v[32:33], v[32:33], v[78:79]
	s_nop 0
	v_pk_add_f32 v[30:31], v[30:31], v[32:33]
	s_nop 0
	v_add_f32_e32 v30, v30, v31
	ds_bpermute_b32 v31, v99, v30
	s_waitcnt lgkmcnt(0)
	v_add_f32_e32 v30, v30, v31
	ds_bpermute_b32 v31, v100, v30
	s_waitcnt lgkmcnt(0)
	v_add_f32_e32 v30, v30, v31
	ds_bpermute_b32 v31, v101, v30
	s_waitcnt lgkmcnt(0)
	v_add_f32_e32 v30, v30, v31
	v_fmamk_f32 v30, v30, 0x3c800000, v247
	v_cmp_gt_f32_e32 vcc, s59, v30
	v_mul_f32_e32 v31, 0x4b800000, v30
	s_nop 0
	v_cndmask_b32_e32 v30, v30, v31, vcc
	v_rsq_f32_e32 v30, v30
	s_nop 0
	v_mul_f32_e32 v31, 0x45800000, v30
	v_cndmask_b32_e32 v30, v30, v31, vcc
	v_mul_f32_e32 v78, 0x3e38aa3b, v30
	v_pk_mul_f32 v[30:31], v[78:79], v[42:43] op_sel_hi:[0,1]
	v_pk_mul_f32 v[32:33], v[78:79], v[44:45] op_sel_hi:[0,1]
	v_pk_mul_f32 v[30:31], v[38:39], v[30:31]
	v_pk_mul_f32 v[38:39], v[78:79], v[46:47] op_sel_hi:[0,1]
	v_pk_mul_f32 v[34:35], v[34:35], v[38:39]
	v_pk_mul_f32 v[38:39], v[78:79], v[48:49] op_sel_hi:[0,1]
	v_pk_mul_f32 v[32:33], v[40:41], v[32:33]
	v_pk_mul_f32 v[36:37], v[36:37], v[38:39]
	ds_bpermute_b32 v38, v99, v30
	ds_bpermute_b32 v39, v99, v31
	ds_bpermute_b32 v40, v99, v32
	ds_bpermute_b32 v41, v99, v33
	ds_bpermute_b32 v42, v99, v34
	ds_bpermute_b32 v43, v99, v35
	ds_bpermute_b32 v44, v99, v36
	ds_bpermute_b32 v45, v99, v37
	s_and_saveexec_b64 s[52:53], s[40:41]
	s_cbranch_execz .LBB0_402
	v_mov_b64_e32 v[46:47], v[166:167]
	v_mov_b64_e32 v[48:49], v[168:169]
	v_mov_b64_e32 v[78:79], v[170:171]
	v_mov_b64_e32 v[80:81], v[172:173]
	v_mov_b64_e32 v[82:83], v[162:163]
	v_mov_b64_e32 v[84:85], v[164:165]
	v_mov_b64_e32 v[86:87], v[158:159]
	v_mov_b64_e32 v[88:89], v[160:161]
	s_waitcnt lgkmcnt(6)
	v_pk_mul_f32 v[38:39], v[46:47], v[38:39]
	s_waitcnt lgkmcnt(4)
	v_pk_mul_f32 v[40:41], v[48:49], v[40:41]
	s_waitcnt lgkmcnt(2)
	v_pk_mul_f32 v[42:43], v[78:79], v[42:43]
	s_waitcnt lgkmcnt(0)
	v_pk_mul_f32 v[44:45], v[80:81], v[44:45]
	v_cndmask_b32_e64 v39, v39, -v39, s[42:43]
	v_cndmask_b32_e64 v38, v38, -v38, s[42:43]
	v_cndmask_b32_e64 v41, v41, -v41, s[42:43]
	v_cndmask_b32_e64 v40, v40, -v40, s[42:43]
	v_cndmask_b32_e64 v42, v42, -v42, s[42:43]
	v_cndmask_b32_e64 v43, v43, -v43, s[42:43]
	v_cndmask_b32_e64 v44, v44, -v44, s[42:43]
	v_cndmask_b32_e64 v45, v45, -v45, s[42:43]
	v_pk_fma_f32 v[36:37], v[36:37], v[84:85], v[44:45]
	v_pk_fma_f32 v[34:35], v[34:35], v[82:83], v[42:43]
	v_pk_fma_f32 v[32:33], v[32:33], v[88:89], v[40:41]
	v_pk_fma_f32 v[30:31], v[30:31], v[86:87], v[38:39]
.LBB0_402:
	s_or_b64 exec, exec, s[52:53]
	v_cvt_pk_bf16_f32 v30, v30, v31
	v_cvt_pk_bf16_f32 v31, v32, v33
	v_cvt_pk_bf16_f32 v32, v34, v35
	v_cvt_pk_bf16_f32 v33, v36, v37
	global_store_dwordx4 v[68:69], v[30:33], off offset:3392
	s_cmp_lg_u32 s32, 0
	s_cbranch_scc1 .Lld_p3_6
	global_load_dwordx4 v[154:157], v[64:65], off offset:16
	global_load_dwordx4 v[150:153], v[64:65], off
	s_waitcnt vmcnt(0)
.Lld_p3_6:
	v_mov_b64_e32 v[30:31], v[154:155]
	v_mov_b64_e32 v[32:33], v[156:157]
	v_mov_b64_e32 v[34:35], v[150:151]
	v_mov_b64_e32 v[36:37], v[152:153]
	s_waitcnt lgkmcnt(6)
	v_and_b32_e32 v39, 0xffff0000, v26
	s_waitcnt lgkmcnt(2)
	v_and_b32_e32 v43, 0xffff0000, v28
	v_lshlrev_b32_e32 v38, 16, v26
	v_and_b32_e32 v41, 0xffff0000, v27
	v_lshlrev_b32_e32 v42, 16, v28
	s_waitcnt lgkmcnt(1)
	v_lshlrev_b32_e32 v44, 16, v29
	s_waitcnt lgkmcnt(0)
	v_and_b32_e32 v45, 0xffff0000, v29
	v_mov_b32_e32 v28, v39
	v_mov_b32_e32 v29, v43
	v_lshlrev_b32_e32 v40, 16, v27
	v_mov_b32_e32 v26, v38
	v_mov_b32_e32 v27, v42
	v_pk_mul_f32 v[28:29], v[28:29], v[28:29]
	v_mov_b32_e32 v46, v41
	v_mov_b32_e32 v47, v45
	v_pk_fma_f32 v[26:27], v[26:27], v[26:27], v[28:29]
	v_mov_b32_e32 v28, v40
	v_mov_b32_e32 v29, v44
	v_pk_mul_f32 v[46:47], v[46:47], v[46:47]
	s_nop 0
	v_pk_fma_f32 v[28:29], v[28:29], v[28:29], v[46:47]
	s_nop 0
	v_pk_add_f32 v[26:27], v[26:27], v[28:29]
	s_nop 0
	v_add_f32_e32 v26, v26, v27
	ds_bpermute_b32 v27, v99, v26
	s_waitcnt lgkmcnt(0)
	v_add_f32_e32 v26, v26, v27
	ds_bpermute_b32 v27, v100, v26
	s_waitcnt lgkmcnt(0)
	v_add_f32_e32 v26, v26, v27
	ds_bpermute_b32 v27, v101, v26
	s_waitcnt lgkmcnt(0)
	v_add_f32_e32 v26, v26, v27
	v_fmamk_f32 v26, v26, 0x3c800000, v247
	v_cmp_gt_f32_e32 vcc, s59, v26
	v_mul_f32_e32 v27, 0x4b800000, v26
	s_nop 0
	v_cndmask_b32_e32 v26, v26, v27, vcc
	v_rsq_f32_e32 v26, v26
	s_nop 0
	v_mul_f32_e32 v27, 0x45800000, v26
	v_cndmask_b32_e32 v46, v26, v27, vcc
	v_pk_mul_f32 v[26:27], v[46:47], v[38:39] op_sel_hi:[0,1]
	v_pk_mul_f32 v[28:29], v[46:47], v[40:41] op_sel_hi:[0,1]
	v_pk_mul_f32 v[26:27], v[34:35], v[26:27]
	v_pk_mul_f32 v[34:35], v[46:47], v[42:43] op_sel_hi:[0,1]
	v_pk_mul_f32 v[30:31], v[30:31], v[34:35]
	v_pk_mul_f32 v[34:35], v[46:47], v[44:45] op_sel_hi:[0,1]
	v_pk_mul_f32 v[28:29], v[36:37], v[28:29]
	v_pk_mul_f32 v[32:33], v[32:33], v[34:35]
	ds_bpermute_b32 v34, v99, v26
	ds_bpermute_b32 v35, v99, v27
	ds_bpermute_b32 v36, v99, v28
	ds_bpermute_b32 v37, v99, v29
	ds_bpermute_b32 v38, v99, v30
	ds_bpermute_b32 v39, v99, v31
	ds_bpermute_b32 v40, v99, v32
	ds_bpermute_b32 v41, v99, v33
	s_and_saveexec_b64 s[52:53], s[40:41]
	s_cbranch_execz .LBB0_404
	v_mov_b64_e32 v[42:43], v[166:167]
	v_mov_b64_e32 v[44:45], v[168:169]
	v_mov_b64_e32 v[46:47], v[170:171]
	v_mov_b64_e32 v[48:49], v[172:173]
	v_mov_b64_e32 v[78:79], v[162:163]
	v_mov_b64_e32 v[80:81], v[164:165]
	v_mov_b64_e32 v[82:83], v[158:159]
	v_mov_b64_e32 v[84:85], v[160:161]
	s_waitcnt lgkmcnt(6)
	v_pk_mul_f32 v[34:35], v[42:43], v[34:35]
	s_waitcnt lgkmcnt(4)
	v_pk_mul_f32 v[36:37], v[44:45], v[36:37]
	s_waitcnt lgkmcnt(2)
	v_pk_mul_f32 v[38:39], v[46:47], v[38:39]
	s_waitcnt lgkmcnt(0)
	v_pk_mul_f32 v[40:41], v[48:49], v[40:41]
	v_cndmask_b32_e64 v35, v35, -v35, s[42:43]
	v_cndmask_b32_e64 v34, v34, -v34, s[42:43]
	v_cndmask_b32_e64 v37, v37, -v37, s[42:43]
	v_cndmask_b32_e64 v36, v36, -v36, s[42:43]
	v_cndmask_b32_e64 v38, v38, -v38, s[42:43]
	v_cndmask_b32_e64 v39, v39, -v39, s[42:43]
	v_cndmask_b32_e64 v40, v40, -v40, s[42:43]
	v_cndmask_b32_e64 v41, v41, -v41, s[42:43]
	v_pk_fma_f32 v[32:33], v[32:33], v[80:81], v[40:41]
	v_pk_fma_f32 v[30:31], v[30:31], v[78:79], v[38:39]
	v_pk_fma_f32 v[28:29], v[28:29], v[84:85], v[36:37]
	v_pk_fma_f32 v[26:27], v[26:27], v[82:83], v[34:35]

.LBB0_410:
	s_or_b64 exec, exec, s[50:51]
	v_mov_b32_e32 v37, v31
	v_mov_b32_e32 v35, v33
	v_mov_b32_e32 v33, v39
	v_mov_b32_e32 v31, v41
	v_mov_b64_e32 v[38:39], v[114:115]
	v_mov_b64_e32 v[40:41], v[116:117]
	v_mov_b64_e32 v[42:43], v[110:111]
	v_mov_b64_e32 v[44:45], v[112:113]
	v_pk_mul_f32 v[36:37], v[28:29], v[36:37] op_sel_hi:[0,1]
	v_pk_mul_f32 v[34:35], v[28:29], v[34:35] op_sel_hi:[0,1]
	v_pk_mul_f32 v[32:33], v[28:29], v[32:33] op_sel_hi:[0,1]
	v_pk_mul_f32 v[30:31], v[28:29], v[30:31] op_sel_hi:[0,1]
	v_pk_mul_f32 v[32:33], v[38:39], v[32:33]
	v_pk_mul_f32 v[36:37], v[42:43], v[36:37]
	v_pk_mul_f32 v[34:35], v[44:45], v[34:35]
	v_pk_mul_f32 v[38:39], v[40:41], v[30:31]
	v_cvt_pk_bf16_f32 v30, v36, v37
	v_cvt_pk_bf16_f32 v31, v34, v35
	v_cvt_pk_bf16_f32 v32, v32, v33
	v_cvt_pk_bf16_f32 v33, v38, v39
	global_store_dwordx4 v[70:71], v[30:33], off
	s_and_saveexec_b64 s[50:51], s[6:7]
	s_cbranch_execz .LBB0_412
	s_load_dwordx2 s[52:53], s[12:13], 0x20
	s_waitcnt lgkmcnt(0)
	v_mov_b32_e32 v27, v23
	v_mov_b32_e32 v23, v29
	v_mov_b32_e32 v25, v19
	v_mov_b32_e32 v19, v21
	s_add_u32 s52, s52, s30
	s_addc_u32 s53, s53, s31
	v_mov_b64_e32 v[28:29], v[122:123]
	v_mov_b64_e32 v[30:31], v[124:125]
	v_mov_b64_e32 v[32:33], v[118:119]
	v_mov_b64_e32 v[34:35], v[120:121]
	v_pk_mul_f32 v[26:27], v[20:21], v[26:27] op_sel_hi:[0,1]
	v_pk_mul_f32 v[24:25], v[20:21], v[24:25] op_sel_hi:[0,1]
	v_pk_mul_f32 v[22:23], v[20:21], v[22:23] op_sel_hi:[0,1]
	v_pk_mul_f32 v[18:19], v[20:21], v[18:19] op_sel_hi:[0,1]
	v_pk_mul_f32 v[22:23], v[28:29], v[22:23]
	v_pk_mul_f32 v[26:27], v[32:33], v[26:27]
	v_pk_mul_f32 v[24:25], v[34:35], v[24:25]
	v_pk_mul_f32 v[28:29], v[30:31], v[18:19]
	v_cvt_pk_bf16_f32 v18, v26, v27
	v_cvt_pk_bf16_f32 v19, v24, v25
	v_cvt_pk_bf16_f32 v20, v22, v23
	v_cvt_pk_bf16_f32 v21, v28, v29
	global_store_dwordx4 v[70:71], v[18:21], off offset:1024
.LBB0_412:
	s_or_b64 exec, exec, s[50:51]
	v_lshlrev_b32_e32 v32, 16, v14
	v_and_b32_e32 v33, 0xffff0000, v14
	v_lshlrev_b32_e32 v34, 16, v15
	v_and_b32_e32 v35, 0xffff0000, v15
	v_lshlrev_b32_e32 v36, 16, v16
	v_and_b32_e32 v37, 0xffff0000, v16
	s_waitcnt lgkmcnt(0)
	v_lshlrev_b32_e32 v27, 16, v17
	v_and_b32_e32 v26, 0xffff0000, v17
	v_mov_b64_e32 v[14:15], v[130:131]
	v_mov_b64_e32 v[16:17], v[132:133]
	v_mov_b64_e32 v[22:23], v[126:127]
	v_mov_b64_e32 v[24:25], v[128:129]
	v_mov_b64_e32 v[18:19], v[138:139]
	v_mov_b64_e32 v[20:21], v[140:141]
	v_mov_b64_e32 v[28:29], v[134:135]
	v_mov_b64_e32 v[30:31], v[136:137]
	s_lshl_b32 s50, s64, 6
	s_and_b32 s50, s50, 0x3ffc0
	s_add_u32 s50, s24, s50
	s_addc_u32 s51, s29, 0
	v_add_f32_e32 v18, v18, v36
	v_add_f32_e32 v28, v28, v32
	v_add_f32_e32 v29, v29, v33
	v_mul_f32_e32 v28, 0xbfb8aa3b, v28
	v_mul_f32_e32 v29, 0xbfb8aa3b, v29
	v_exp_f32_e32 v28, v28
	v_exp_f32_e32 v29, v29
	v_lshlrev_b32_e32 v32, 16, v10
	v_and_b32_e32 v33, 0xffff0000, v10
	v_pk_add_f32 v[22:23], v[22:23], v[32:33]
	v_pk_add_f32 v[28:29], v[28:29], 1.0 op_sel_hi:[1,0]
	v_add_f32_e32 v19, v19, v37
	v_mul_f32_e32 v18, 0xbfb8aa3b, v18
	v_mul_f32_e32 v19, 0xbfb8aa3b, v19
	v_exp_f32_e32 v18, v18
	v_rcp_f32_e32 v29, v29
	v_exp_f32_e32 v19, v19
	v_rcp_f32_e32 v28, v28
	v_add_f32_e32 v10, v30, v34
	v_mul_f32_e32 v10, 0xbfb8aa3b, v10
	v_pk_mul_f32 v[22:23], v[22:23], v[28:29]
	v_exp_f32_e32 v28, v10
	v_add_f32_e32 v10, v31, v35
	v_mul_f32_e32 v10, 0xbfb8aa3b, v10
	v_exp_f32_e32 v29, v10
	v_lshlrev_b32_e32 v10, 16, v11
	v_and_b32_e32 v11, 0xffff0000, v11
	v_pk_add_f32 v[10:11], v[24:25], v[10:11]
	v_pk_add_f32 v[24:25], v[28:29], 1.0 op_sel_hi:[1,0]
	v_pk_add_f32 v[18:19], v[18:19], 1.0 op_sel_hi:[1,0]
	s_nop 0
	v_rcp_f32_e32 v25, v25
	s_nop 0
	v_rcp_f32_e32 v24, v24
	s_nop 0
	v_pk_mul_f32 v[10:11], v[10:11], v[24:25]
	v_lshlrev_b32_e32 v24, 16, v12
	v_and_b32_e32 v25, 0xffff0000, v12
	v_pk_add_f32 v[14:15], v[14:15], v[24:25]
	s_nop 0
	v_rcp_f32_e32 v19, v19
	s_nop 0
	v_rcp_f32_e32 v18, v18
	v_add_f32_e32 v12, v20, v27
	v_mul_f32_e32 v12, 0xbfb8aa3b, v12
	v_pk_mul_f32 v[14:15], v[14:15], v[18:19]
	v_exp_f32_e32 v18, v12
	v_add_f32_e32 v12, v21, v26
	v_mul_f32_e32 v12, 0xbfb8aa3b, v12
	v_exp_f32_e32 v19, v12
	v_lshlrev_b32_e32 v12, 16, v13
	v_and_b32_e32 v13, 0xffff0000, v13
	v_pk_add_f32 v[12:13], v[16:17], v[12:13]
	v_pk_add_f32 v[16:17], v[18:19], 1.0 op_sel_hi:[1,0]
	v_cvt_pk_bf16_f32 v14, v14, v15
	v_and_b32_e32 v25, 0xffff0000, v9
	v_mov_b32_e32 v27, v25
	v_rcp_f32_e32 v17, v17
	s_nop 0
	v_rcp_f32_e32 v16, v16
	s_nop 0
	v_pk_mul_f32 v[16:17], v[12:13], v[16:17]
	v_cvt_pk_bf16_f32 v12, v22, v23
	v_cvt_pk_bf16_f32 v13, v10, v11
	v_cvt_pk_bf16_f32 v15, v16, v17
	global_store_dwordx4 v[70:71], v[12:15], off offset:1344
	v_mov_b64_e32 v[10:11], v[146:147]
	s_nop 1
	v_mov_b64_e32 v[12:13], v[148:149]
	v_mov_b64_e32 v[14:15], v[142:143]
	v_mov_b64_e32 v[16:17], v[144:145]
	v_and_b32_e32 v19, 0xffff0000, v6
	v_and_b32_e32 v23, 0xffff0000, v8
	v_lshlrev_b32_e32 v18, 16, v6
	v_and_b32_e32 v21, 0xffff0000, v7
	v_lshlrev_b32_e32 v22, 16, v8
	v_lshlrev_b32_e32 v24, 16, v9
	v_mov_b32_e32 v8, v19
	v_mov_b32_e32 v9, v23
	v_lshlrev_b32_e32 v20, 16, v7
	v_mov_b32_e32 v6, v18
	v_mov_b32_e32 v7, v22
	v_pk_mul_f32 v[8:9], v[8:9], v[8:9]
	v_mov_b32_e32 v26, v21
	v_pk_fma_f32 v[6:7], v[6:7], v[6:7], v[8:9]
	v_mov_b32_e32 v8, v20
	v_mov_b32_e32 v9, v24
	v_pk_mul_f32 v[26:27], v[26:27], v[26:27]
	s_nop 0
	v_pk_fma_f32 v[8:9], v[8:9], v[8:9], v[26:27]
	s_nop 0
	v_pk_add_f32 v[6:7], v[6:7], v[8:9]
	s_nop 0
	v_add_f32_e32 v6, v6, v7
	ds_bpermute_b32 v7, v99, v6
	s_waitcnt lgkmcnt(0)
	v_add_f32_e32 v6, v6, v7
	ds_bpermute_b32 v7, v100, v6
	s_waitcnt lgkmcnt(0)
	v_add_f32_e32 v6, v6, v7
	ds_bpermute_b32 v7, v101, v6
	s_waitcnt lgkmcnt(0)
	v_add_f32_e32 v6, v6, v7
	v_fmamk_f32 v6, v6, 0x3c800000, v247
	v_cmp_gt_f32_e32 vcc, s59, v6
	v_mul_f32_e32 v7, 0x4b800000, v6
	s_nop 0
	v_cndmask_b32_e32 v6, v6, v7, vcc
	v_rsq_f32_e32 v6, v6
	s_nop 0
	v_mul_f32_e32 v7, 0x45800000, v6
	v_cndmask_b32_e32 v6, v6, v7, vcc
	v_mul_f32_e32 v26, 0x3e38aa3b, v6
	v_pk_mul_f32 v[6:7], v[26:27], v[18:19] op_sel_hi:[0,1]
	v_pk_mul_f32 v[8:9], v[26:27], v[20:21] op_sel_hi:[0,1]
	v_pk_mul_f32 v[6:7], v[14:15], v[6:7]
	v_pk_mul_f32 v[14:15], v[26:27], v[22:23] op_sel_hi:[0,1]
	v_pk_mul_f32 v[10:11], v[10:11], v[14:15]
	v_pk_mul_f32 v[14:15], v[26:27], v[24:25] op_sel_hi:[0,1]
	v_pk_mul_f32 v[8:9], v[16:17], v[8:9]
	v_pk_mul_f32 v[12:13], v[12:13], v[14:15]
	ds_bpermute_b32 v14, v99, v6
	ds_bpermute_b32 v15, v99, v7
	ds_bpermute_b32 v16, v99, v8
	ds_bpermute_b32 v17, v99, v9
	ds_bpermute_b32 v18, v99, v10
	ds_bpermute_b32 v19, v99, v11
	ds_bpermute_b32 v20, v99, v12
	ds_bpermute_b32 v21, v99, v13
	s_and_saveexec_b64 s[52:53], s[40:41]
	s_cbranch_execz .LBB0_414
; DI void unpack8(const u32x4 w, float (&f)[8]) { f[0] = bflo(w.x); f[1] = bfhi(w.x); f[2] = bflo(w.y); f[3] = bfhi(w.y); f[4] = bflo(w.z); f[5] = bfhi(w.z); f[6] = bflo(w.w); f[7] = bfhi(w.w); }
; DI u32x4 pack8(const float (&f)[8]) { u32x4 w; w.x = pk2(f[0], f[1]); w.y = pk2(f[2], f[3]); w.z = pk2(f[4], f[5]); w.w = pk2(f[6], f[7]); return w; }
; DI float ssq8(const float (&f)[8]) { return ((f[0] * f[0] + f[1] * f[1]) + (f[2] * f[2] + f[3] * f[3])) + ((f[4] * f[4] + f[5] * f[5]) + (f[6] * f[6] + f[7] * f[7])); }
;     float q[8]; unpack8(w, q);
;     float ss = ssq8(q); ss += __shfl_xor(ss, 1); ss += __shfl_xor(ss, 2); ss += __shfl_xor(ss, 4);
;     const float r = rsqrtf(ss * (1.f / 64.f) + EPS) * oscale;
;     const int sub = lane & 7;
;     float g[8]; load8f(gain + 8 * sub, g);
;     float y[8], p[8];
; #pragma unroll
;     for (int e = 0; e < 8; ++e) y[e] = q[e] * r * g[e];
; #pragma unroll
;     for (int e = 0; e < 8; ++e) p[e] = __shfl_xor(y[e], 1);
;     if (sub < 2) {
;         float c[8], s[8]; load8f(rt, c); load8f(rt + 8, s);
; #pragma unroll
;         for (int e = 0; e < 8; ++e) y[e] = (sub == 0) ? (y[e] * c[e] - p[e] * s[e]) : (y[e] * c[e] + p[e] * s[e]);
;     }
;     return pack8(y);
	v_mov_b64_e32 v[22:23], v[182:183]
	v_mov_b64_e32 v[24:25], v[184:185]
	v_mov_b64_e32 v[26:27], v[186:187]
	v_mov_b64_e32 v[28:29], v[188:189]
	v_mov_b64_e32 v[30:31], v[178:179]
	v_mov_b64_e32 v[32:33], v[180:181]
	v_mov_b64_e32 v[34:35], v[174:175]
	v_mov_b64_e32 v[36:37], v[176:177]
	s_waitcnt lgkmcnt(6)
	v_pk_mul_f32 v[14:15], v[22:23], v[14:15]
	s_waitcnt lgkmcnt(4)
	v_pk_mul_f32 v[16:17], v[24:25], v[16:17]
	s_waitcnt lgkmcnt(2)
	v_pk_mul_f32 v[18:19], v[26:27], v[18:19]
	s_waitcnt lgkmcnt(0)
	v_pk_mul_f32 v[20:21], v[28:29], v[20:21]
	v_cndmask_b32_e64 v15, v15, -v15, s[42:43]
	v_cndmask_b32_e64 v14, v14, -v14, s[42:43]
	v_cndmask_b32_e64 v17, v17, -v17, s[42:43]
	v_cndmask_b32_e64 v16, v16, -v16, s[42:43]
	v_cndmask_b32_e64 v18, v18, -v18, s[42:43]
	v_cndmask_b32_e64 v19, v19, -v19, s[42:43]
	v_cndmask_b32_e64 v20, v20, -v20, s[42:43]
	v_cndmask_b32_e64 v21, v21, -v21, s[42:43]
	v_pk_fma_f32 v[12:13], v[12:13], v[32:33], v[20:21]
	v_pk_fma_f32 v[10:11], v[10:11], v[30:31], v[18:19]
	v_pk_fma_f32 v[8:9], v[8:9], v[36:37], v[16:17]
	v_pk_fma_f32 v[6:7], v[6:7], v[34:35], v[14:15]
.LBB0_414:
	s_or_b64 exec, exec, s[52:53]
	v_cvt_pk_bf16_f32 v6, v6, v7
	v_cvt_pk_bf16_f32 v7, v8, v9
	v_cvt_pk_bf16_f32 v8, v10, v11
	v_cvt_pk_bf16_f32 v9, v12, v13
	global_store_dwordx4 v[70:71], v[6:9], off offset:3392
	s_nop 1
	v_mov_b64_e32 v[6:7], v[154:155]
	v_mov_b64_e32 v[8:9], v[156:157]
	v_mov_b64_e32 v[10:11], v[150:151]
	v_mov_b64_e32 v[12:13], v[152:153]
	s_waitcnt lgkmcnt(6)
	v_and_b32_e32 v15, 0xffff0000, v2
	s_waitcnt lgkmcnt(2)
	v_and_b32_e32 v19, 0xffff0000, v4
	v_lshlrev_b32_e32 v14, 16, v2
	v_and_b32_e32 v17, 0xffff0000, v3
	v_lshlrev_b32_e32 v18, 16, v4
	s_waitcnt lgkmcnt(1)
	v_lshlrev_b32_e32 v20, 16, v5
	s_waitcnt lgkmcnt(0)
	v_and_b32_e32 v21, 0xffff0000, v5
	v_mov_b32_e32 v4, v15
	v_mov_b32_e32 v5, v19
	v_lshlrev_b32_e32 v16, 16, v3
	v_mov_b32_e32 v2, v14
	v_mov_b32_e32 v3, v18
	v_pk_mul_f32 v[4:5], v[4:5], v[4:5]
	v_mov_b32_e32 v22, v17
	v_mov_b32_e32 v23, v21
	v_pk_fma_f32 v[2:3], v[2:3], v[2:3], v[4:5]
	v_mov_b32_e32 v4, v16
	v_mov_b32_e32 v5, v20
	v_pk_mul_f32 v[22:23], v[22:23], v[22:23]
	s_nop 0
	v_pk_fma_f32 v[4:5], v[4:5], v[4:5], v[22:23]
	s_nop 0
	v_pk_add_f32 v[2:3], v[2:3], v[4:5]
	s_nop 0
	v_add_f32_e32 v2, v2, v3
	ds_bpermute_b32 v3, v99, v2
	s_waitcnt lgkmcnt(0)
	v_add_f32_e32 v2, v2, v3
	ds_bpermute_b32 v3, v100, v2
	s_waitcnt lgkmcnt(0)
	v_add_f32_e32 v2, v2, v3
	ds_bpermute_b32 v3, v101, v2
	s_waitcnt lgkmcnt(0)
	v_add_f32_e32 v2, v2, v3
	v_fmamk_f32 v2, v2, 0x3c800000, v247
	v_cmp_gt_f32_e32 vcc, s59, v2
	v_mul_f32_e32 v3, 0x4b800000, v2
	s_nop 0
	v_cndmask_b32_e32 v2, v2, v3, vcc
	v_rsq_f32_e32 v2, v2
	s_nop 0
	v_mul_f32_e32 v3, 0x45800000, v2
	v_cndmask_b32_e32 v22, v2, v3, vcc
	v_pk_mul_f32 v[2:3], v[22:23], v[14:15] op_sel_hi:[0,1]
	v_pk_mul_f32 v[4:5], v[22:23], v[16:17] op_sel_hi:[0,1]
	v_pk_mul_f32 v[2:3], v[10:11], v[2:3]
	v_pk_mul_f32 v[10:11], v[22:23], v[18:19] op_sel_hi:[0,1]
	v_pk_mul_f32 v[6:7], v[6:7], v[10:11]
	v_pk_mul_f32 v[10:11], v[22:23], v[20:21] op_sel_hi:[0,1]
	v_pk_mul_f32 v[4:5], v[12:13], v[4:5]
	v_pk_mul_f32 v[8:9], v[8:9], v[10:11]
	ds_bpermute_b32 v10, v99, v2
	ds_bpermute_b32 v11, v99, v3
	ds_bpermute_b32 v12, v99, v4
	ds_bpermute_b32 v13, v99, v5
	ds_bpermute_b32 v14, v99, v6
	ds_bpermute_b32 v15, v99, v7
	ds_bpermute_b32 v16, v99, v8
	ds_bpermute_b32 v17, v99, v9
	s_and_saveexec_b64 s[52:53], s[40:41]
	s_cbranch_execz .LBB0_416
	v_mov_b64_e32 v[18:19], v[182:183]
	v_mov_b64_e32 v[20:21], v[184:185]
	v_mov_b64_e32 v[22:23], v[186:187]
	v_mov_b64_e32 v[24:25], v[188:189]
	v_mov_b64_e32 v[26:27], v[178:179]
	v_mov_b64_e32 v[28:29], v[180:181]
	v_mov_b64_e32 v[30:31], v[174:175]
	v_mov_b64_e32 v[32:33], v[176:177]
	s_waitcnt lgkmcnt(6)
	v_pk_mul_f32 v[10:11], v[18:19], v[10:11]
	s_waitcnt lgkmcnt(4)
	v_pk_mul_f32 v[12:13], v[20:21], v[12:13]
	s_waitcnt lgkmcnt(2)
	v_pk_mul_f32 v[14:15], v[22:23], v[14:15]
	s_waitcnt lgkmcnt(0)
	v_pk_mul_f32 v[16:17], v[24:25], v[16:17]
	v_cndmask_b32_e64 v11, v11, -v11, s[42:43]
	v_cndmask_b32_e64 v10, v10, -v10, s[42:43]
	v_cndmask_b32_e64 v13, v13, -v13, s[42:43]
	v_cndmask_b32_e64 v12, v12, -v12, s[42:43]
	v_cndmask_b32_e64 v14, v14, -v14, s[42:43]
	v_cndmask_b32_e64 v15, v15, -v15, s[42:43]
	v_cndmask_b32_e64 v16, v16, -v16, s[42:43]
	v_cndmask_b32_e64 v17, v17, -v17, s[42:43]
	v_pk_fma_f32 v[8:9], v[8:9], v[28:29], v[16:17]
	v_pk_fma_f32 v[6:7], v[6:7], v[26:27], v[14:15]
	v_pk_fma_f32 v[4:5], v[4:5], v[32:33], v[12:13]
	v_pk_fma_f32 v[2:3], v[2:3], v[30:31], v[10:11]

; #define LAS __attribute__((address_space(3)))
; DI void nsa_unit(LAS char* lds, int b, int g, int qb, const bf16* Z, const bf16* KC, const bf16* VC, bf16* On, int tid, int lane, int wave) {
;     ...
;         for (int qi = 0; qi < 8; ++qi) {
;             const int q = wave * 8 + qi;
;             float v = -INFINITY;
;             if (n <= qb) {
;                 v = ((impH[(0 * 64 + q) * 64 + n] + impH[(1 * 64 + q) * 64 + n]) + impH[(2 * 64 + q) * 64 + n]) + impH[(3 * 64 + q) * 64 + n];
;                 if (n == 0 || n == qb || n == qb - 1) v = 1e6f;
;             }
;             LAS float* vs = (LAS float*)(lds + ATT_SEL_OFF + 512) + wave * 64;
;             vs[n] = v;
;             int cnt = 0;
; #pragma unroll 4
;             for (int m4 = 0; m4 < 16; ++m4) {
;                 const f32x4 vm = *(const LAS f32x4*)(vs + 4 * m4);
; #pragma unroll
;                 for (int e = 0; e < 4; ++e) { const int m = 4 * m4 + e; cnt += (vm[e] > v || (vm[e] == v && m < n)) ? 1 : 0; }
;             }
;             const bool sel = (cnt < 16) && (n <= qb);
;             const unsigned long long mk = __ballot(sel);
;             if (lane == 0) selm[q] = mk;
;         }
.LBB0_1086:
	s_or_b64 exec, exec, s[18:19]
	v_cndmask_b32_e64 v34, 0, v0, s[16:17]
	s_mov_b32 s31, 0
	s_mov_b32 s51, 0x40000000
.Ltk_bit:
	s_or_b32 s52, s31, s51
	v_cmp_le_u32_e32 vcc, s52, v34
	s_bcnt1_i32_b64 s18, vcc
	s_cmp_ge_u32 s18, 16
	s_cselect_b32 s31, s52, s31
	s_lshr_b32 s51, s51, 1
	s_cmp_lg_u32 s51, 0
	s_cbranch_scc1 .Ltk_bit
	v_cmp_lt_u32_e32 vcc, s31, v34
	s_bcnt1_i32_b64 s51, vcc
	s_mov_b64 s[20:21], vcc
	v_cmp_eq_u32_e64 s[18:19], s31, v34
	s_sub_i32 s51, 16, s51
	s_nop 0
	v_mbcnt_lo_u32_b32 v35, s18, 0
	v_mbcnt_hi_u32_b32 v35, s19, v35
	v_cmp_gt_u32_e32 vcc, s51, v35
	s_and_b64 s[18:19], s[18:19], vcc
	s_or_b64 s[20:21], s[20:21], s[18:19]
	s_and_b64 s[20:21], s[20:21], s[16:17]
	s_and_saveexec_b64 s[18:19], s[40:41]
	s_cbranch_execz .LBB0_1083
	s_lshl_b32 s30, s30, 3
	s_add_i32 s30, s30, 0
	s_add_i32 s30, s30, 0x1c000
	v_mov_b32_e32 v0, s30
	v_mov_b64_e32 v[34:35], s[20:21]
	ds_write_b64 v0, v[34:35]
	s_branch .LBB0_1083

; __global__ void __launch_bounds__(NTHR, 2) hybrid_fwd(Args args) {
	.amdhsa_kernel _Z10hybrid_fwd4Args
		.amdhsa_group_segment_fixed_size 0
		.amdhsa_private_segment_fixed_size 0
		.amdhsa_kernarg_size 512
		.amdhsa_user_sgpr_count 2
		.amdhsa_user_sgpr_dispatch_ptr 0
		.amdhsa_user_sgpr_queue_ptr 0
		.amdhsa_user_sgpr_kernarg_segment_ptr 1
		.amdhsa_user_sgpr_dispatch_id 0
		.amdhsa_user_sgpr_kernarg_preload_length 0
		.amdhsa_user_sgpr_kernarg_preload_offset 0
		.amdhsa_user_sgpr_private_segment_size 0
		.amdhsa_uses_dynamic_stack 0
		.amdhsa_enable_private_segment 0
		.amdhsa_system_sgpr_workgroup_id_x 1
		.amdhsa_system_sgpr_workgroup_id_y 0
		.amdhsa_system_sgpr_workgroup_id_z 0
		.amdhsa_system_sgpr_workgroup_info 0
		.amdhsa_system_vgpr_workitem_id 2
		.amdhsa_next_free_vgpr 256
		.amdhsa_next_free_sgpr 102
		.amdhsa_accum_offset 256
		.amdhsa_reserve_vcc 1
		.amdhsa_float_round_mode_32 0
		.amdhsa_float_round_mode_16_64 0
		.amdhsa_float_denorm_mode_32 3
		.amdhsa_float_denorm_mode_16_64 3
		.amdhsa_dx10_clamp 1
		.amdhsa_ieee_mode 1
		.amdhsa_fp16_overflow 0
		.amdhsa_tg_split 0
		.amdhsa_exception_fp_ieee_invalid_op 0
		.amdhsa_exception_fp_denorm_src 0
		.amdhsa_exception_fp_ieee_div_zero 0
		.amdhsa_exception_fp_ieee_overflow 0
		.amdhsa_exception_fp_ieee_underflow 0
		.amdhsa_exception_fp_ieee_inexact 0
		.amdhsa_exception_int_div_zero 0
	.end_amdhsa_kernel

; __global__ void __launch_bounds__(NTHR, 2) hybrid_fwd(Args args) {
;     extern __shared__ __attribute__((aligned(16))) unsigned char lds_raw[];
amdhsa.kernels:
  - .agpr_count:     0
    .args:
      - .offset:         0
        .size:           256
        .value_kind:     by_value
      - .offset:         256
        .size:           4
        .value_kind:     hidden_block_count_x
      - .offset:         260
        .size:           4
        .value_kind:     hidden_block_count_y
      - .offset:         264
        .size:           4
        .value_kind:     hidden_block_count_z
      - .offset:         268
        .size:           2
        .value_kind:     hidden_group_size_x
      - .offset:         270
        .size:           2
        .value_kind:     hidden_group_size_y
      - .offset:         272
        .size:           2
        .value_kind:     hidden_group_size_z
      - .offset:         274
        .size:           2
        .value_kind:     hidden_remainder_x
      - .offset:         276
        .size:           2
        .value_kind:     hidden_remainder_y
      - .offset:         278
        .size:           2
        .value_kind:     hidden_remainder_z
      - .offset:         296
        .size:           8
        .value_kind:     hidden_global_offset_x
      - .offset:         304
        .size:           8
        .value_kind:     hidden_global_offset_y
      - .offset:         312
        .size:           8
        .value_kind:     hidden_global_offset_z
      - .offset:         320
        .size:           2
        .value_kind:     hidden_grid_dims
      - .offset:         344
        .size:           8
        .value_kind:     hidden_multigrid_sync_arg
      - .offset:         376
        .size:           4
        .value_kind:     hidden_dynamic_lds_size
    .group_segment_fixed_size: 0
    .kernarg_segment_align: 8
    .kernarg_segment_size: 512
    .language:       OpenCL C
    .language_version:
      - 2
      - 0
    .max_flat_workgroup_size: 512
    .name:           _Z10hybrid_fwd4Args
    .private_segment_fixed_size: 0
    .sgpr_count:     108
    .sgpr_spill_count: 107
    .symbol:         _Z10hybrid_fwd4Args.kd
    .uniform_work_group_size: 1
    .uses_dynamic_stack: false
    .vgpr_count:     256
    .vgpr_spill_count: 0
    .wavefront_size: 64
